# v26: v24 + scan chunk A->B boundary: next chunk's first operand ds_reads issued with the y read-back right after the barrier
# baseline (speedup 1.0000x reference)
.LBB0_1197:
	s_or_b64 exec, exec, s[16:17]
	s_waitcnt lgkmcnt(0)
	s_barrier
	ds_read_b32 v182, v99 offset:43008
	ds_read_b128 v[32:35], v76 offset:22016
	ds_read_b128 v[36:39], v76 offset:21760
	ds_read_b128 v[40:43], v76 offset:21504
	ds_read_b32 v44, v97 offset:22784
	ds_read_b128 v[140:143], v76 offset:22272
	ds_read_b128 v[144:147], v76 offset:22528
	ds_read_b128 v[108:111], v76 offset:23360
	ds_read_b128 v[112:115], v76 offset:23104
	ds_read_b128 v[116:119], v76 offset:22848
	ds_read_b32 v120, v97 offset:24128
	ds_read_b128 v[56:59], v76 offset:23616
	ds_read_b128 v[64:67], v76 offset:23872
	s_lshl_b32 s6, s20, 4
	v_lshl_add_u64 v[180:181], v[72:73], 0, s[6:7]
	v_lshlrev_b64 v[180:181], 11, v[180:181]
	v_lshl_add_u64 v[180:181], v[86:87], 0, v[180:181]
	s_waitcnt lgkmcnt(12)
	global_store_dword v[180:181], v182, off nt
	s_cmpk_gt_u32 s20, 0x7c
	s_cbranch_scc1 .LBB0_1201
	s_add_i32 s16, s6, 48
	s_add_u32 s16, s8, s16
	s_addc_u32 s17, s9, 0
	v_mov_b32_e32 v17, s17
	v_or_b32_e32 v16, s16, v75
	v_lshl_add_u64 v[24:25], s[16:17], 0, v[70:71]
	v_lshlrev_b64 v[20:21], 10, v[16:17]
	v_lshlrev_b64 v[24:25], 11, v[24:25]
	v_lshl_add_u64 v[16:17], v[78:79], 0, v[20:21]
	v_lshl_add_u64 v[20:21], v[80:81], 0, v[20:21]
	v_lshl_add_u64 v[24:25], v[82:83], 0, v[24:25]
	global_load_dwordx4 v[16:19], v[16:17], off
	s_nop 0
	global_load_dwordx4 v[20:23], v[20:21], off
	s_nop 0
	global_load_dwordx4 v[24:27], v[24:25], off
	s_and_saveexec_b64 s[18:19], s[4:5]
	s_cbranch_execz .LBB0_1200
	v_mov_b32_e32 v29, s17
	v_or_b32_e32 v28, s16, v74
	v_lshlrev_b64 v[28:29], 10, v[28:29]
	v_lshl_add_u64 v[28:29], v[84:85], 0, v[28:29]
	global_load_dwordx4 v[28:31], v[28:29], off

.LBB0_1201:
	s_waitcnt lgkmcnt(11)
	v_pk_mul_f32 v[122:123], v[60:61], v[32:33]
	v_pk_fma_f32 v[122:123], v[52:53], v[34:35], v[122:123]
	s_waitcnt lgkmcnt(8)
	v_add_f32_e32 v49, v122, v123
	v_pk_mul_f32 v[122:123], v[36:37], v[44:45] op_sel_hi:[1,0]
	v_pk_mul_f32 v[138:139], v[38:39], v[44:45] op_sel_hi:[1,0]
	v_add_f32_dpp v49, v49, v49 quad_perm:[1,0,3,2] row_mask:0xf bank_mask:0xf bound_ctrl:1
	v_pk_fma_f32 v[60:61], v[60:61], v[40:41], v[122:123]
	v_pk_fma_f32 v[52:53], v[52:53], v[42:43], v[138:139]
	v_add_f32_dpp v49, v49, v49 quad_perm:[2,3,0,1] row_mask:0xf bank_mask:0xf bound_ctrl:1
	ds_read_b128 v[124:127], v76 offset:24704
	ds_read_b128 v[128:131], v76 offset:24448
	v_add_f32_dpp v49, v49, v49 row_half_mirror row_mask:0xf bank_mask:0xf bound_ctrl:1
	ds_read_b128 v[132:135], v76 offset:24192
	ds_read_b32 v136, v97 offset:25472
	v_add_f32_dpp v48, v49, v49 row_ror:8 row_mask:0xf bank_mask:0xf bound_ctrl:1
	s_waitcnt lgkmcnt(6)
	v_pk_fma_f32 v[60:61], v[140:141], v[48:49], v[60:61] op_sel_hi:[1,0,1] neg_lo:[0,1,0] neg_hi:[0,1,0]
	v_pk_fma_f32 v[52:53], v[142:143], v[48:49], v[52:53] op_sel_hi:[1,0,1] neg_lo:[0,1,0] neg_hi:[0,1,0]
	v_pk_mul_f32 v[122:123], v[60:61], v[108:109]
	v_pk_fma_f32 v[122:123], v[52:53], v[110:111], v[122:123]
	v_add_f32_e32 v49, v122, v123
	v_pk_mul_f32 v[122:123], v[60:61], v[144:145]
	v_pk_fma_f32 v[122:123], v[52:53], v[146:147], v[122:123]
	ds_read_b128 v[140:143], v76 offset:24960
	v_add_f32_dpp v49, v49, v49 quad_perm:[1,0,3,2] row_mask:0xf bank_mask:0xf bound_ctrl:1
	v_add_f32_e32 v90, v122, v123
	v_pk_mul_f32 v[122:123], v[112:113], v[120:121] op_sel_hi:[1,0]
	ds_read_b128 v[144:147], v76 offset:25216
	v_add_f32_dpp v49, v49, v49 quad_perm:[2,3,0,1] row_mask:0xf bank_mask:0xf bound_ctrl:1
	v_pk_mul_f32 v[138:139], v[114:115], v[120:121] op_sel_hi:[1,0]
	v_pk_fma_f32 v[60:61], v[60:61], v[116:117], v[122:123]
	ds_read_b128 v[32:35], v76 offset:26048
	v_add_f32_dpp v49, v49, v49 row_half_mirror row_mask:0xf bank_mask:0xf bound_ctrl:1
	v_pk_fma_f32 v[52:53], v[52:53], v[118:119], v[138:139]
	ds_read_b128 v[36:39], v76 offset:25792
	ds_read_b128 v[40:43], v76 offset:25536
	ds_read_b32 v44, v97 offset:26816
	v_add_f32_dpp v48, v49, v49 row_ror:8 row_mask:0xf bank_mask:0xf bound_ctrl:1
	s_waitcnt lgkmcnt(6)
	v_pk_fma_f32 v[60:61], v[56:57], v[48:49], v[60:61] op_sel_hi:[1,0,1] neg_lo:[0,1,0] neg_hi:[0,1,0]
	v_pk_fma_f32 v[52:53], v[58:59], v[48:49], v[52:53] op_sel_hi:[1,0,1] neg_lo:[0,1,0] neg_hi:[0,1,0]
	v_pk_mul_f32 v[122:123], v[60:61], v[124:125]
	v_pk_fma_f32 v[122:123], v[52:53], v[126:127], v[122:123]
	v_add_f32_e32 v49, v122, v123
	v_pk_mul_f32 v[122:123], v[60:61], v[64:65]
	v_pk_fma_f32 v[122:123], v[52:53], v[66:67], v[122:123]
	ds_read_b128 v[56:59], v76 offset:26304
	v_add_f32_dpp v49, v49, v49 quad_perm:[1,0,3,2] row_mask:0xf bank_mask:0xf bound_ctrl:1
	v_add_f32_e32 v91, v122, v123
	v_pk_mul_f32 v[122:123], v[128:129], v[136:137] op_sel_hi:[1,0]
	ds_read_b128 v[64:67], v76 offset:26560
	v_add_f32_dpp v49, v49, v49 quad_perm:[2,3,0,1] row_mask:0xf bank_mask:0xf bound_ctrl:1
	v_pk_mul_f32 v[138:139], v[130:131], v[136:137] op_sel_hi:[1,0]
	v_pk_fma_f32 v[60:61], v[60:61], v[132:133], v[122:123]
	ds_read_b128 v[108:111], v76 offset:27392
	v_add_f32_dpp v49, v49, v49 row_half_mirror row_mask:0xf bank_mask:0xf bound_ctrl:1
	v_pk_fma_f32 v[52:53], v[52:53], v[134:135], v[138:139]
	ds_read_b128 v[112:115], v76 offset:27136
	ds_read_b128 v[116:119], v76 offset:26880
	ds_read_b32 v120, v97 offset:28160
	v_add_f32_dpp v48, v49, v49 row_ror:8 row_mask:0xf bank_mask:0xf bound_ctrl:1
	s_waitcnt lgkmcnt(6)
	v_pk_fma_f32 v[60:61], v[140:141], v[48:49], v[60:61] op_sel_hi:[1,0,1] neg_lo:[0,1,0] neg_hi:[0,1,0]
	v_pk_fma_f32 v[52:53], v[142:143], v[48:49], v[52:53] op_sel_hi:[1,0,1] neg_lo:[0,1,0] neg_hi:[0,1,0]
	v_pk_mul_f32 v[122:123], v[60:61], v[32:33]
	v_pk_fma_f32 v[122:123], v[52:53], v[34:35], v[122:123]
	v_add_f32_e32 v49, v122, v123
	v_pk_mul_f32 v[122:123], v[60:61], v[144:145]
	v_pk_fma_f32 v[122:123], v[52:53], v[146:147], v[122:123]
	ds_read_b128 v[140:143], v76 offset:27648
	v_add_f32_dpp v49, v49, v49 quad_perm:[1,0,3,2] row_mask:0xf bank_mask:0xf bound_ctrl:1
	v_add_f32_e32 v92, v122, v123
	v_pk_mul_f32 v[122:123], v[36:37], v[44:45] op_sel_hi:[1,0]
	ds_read_b128 v[144:147], v76 offset:27904
	v_add_f32_dpp v49, v49, v49 quad_perm:[2,3,0,1] row_mask:0xf bank_mask:0xf bound_ctrl:1
	v_pk_mul_f32 v[138:139], v[38:39], v[44:45] op_sel_hi:[1,0]
	v_pk_fma_f32 v[60:61], v[60:61], v[40:41], v[122:123]
	ds_read_b128 v[124:127], v76 offset:28736
	v_add_f32_dpp v49, v49, v49 row_half_mirror row_mask:0xf bank_mask:0xf bound_ctrl:1
	v_pk_fma_f32 v[52:53], v[52:53], v[42:43], v[138:139]
	ds_read_b128 v[128:131], v76 offset:28480
	ds_read_b128 v[132:135], v76 offset:28224
	ds_read_b32 v136, v97 offset:29504
	v_add_f32_dpp v48, v49, v49 row_ror:8 row_mask:0xf bank_mask:0xf bound_ctrl:1
	s_waitcnt lgkmcnt(6)
	v_pk_fma_f32 v[60:61], v[56:57], v[48:49], v[60:61] op_sel_hi:[1,0,1] neg_lo:[0,1,0] neg_hi:[0,1,0]
	v_pk_fma_f32 v[52:53], v[58:59], v[48:49], v[52:53] op_sel_hi:[1,0,1] neg_lo:[0,1,0] neg_hi:[0,1,0]
	v_pk_mul_f32 v[122:123], v[60:61], v[108:109]
	v_pk_fma_f32 v[122:123], v[52:53], v[110:111], v[122:123]
	v_add_f32_e32 v49, v122, v123
	v_pk_mul_f32 v[122:123], v[60:61], v[64:65]
	v_pk_fma_f32 v[122:123], v[52:53], v[66:67], v[122:123]
	ds_read_b128 v[56:59], v76 offset:28992
	v_add_f32_dpp v49, v49, v49 quad_perm:[1,0,3,2] row_mask:0xf bank_mask:0xf bound_ctrl:1
	v_add_f32_e32 v93, v122, v123
	v_pk_mul_f32 v[122:123], v[112:113], v[120:121] op_sel_hi:[1,0]
	ds_read_b128 v[64:67], v76 offset:29248
	v_add_f32_dpp v49, v49, v49 quad_perm:[2,3,0,1] row_mask:0xf bank_mask:0xf bound_ctrl:1
	v_pk_mul_f32 v[138:139], v[114:115], v[120:121] op_sel_hi:[1,0]
	v_pk_fma_f32 v[60:61], v[60:61], v[116:117], v[122:123]
	ds_read_b128 v[32:35], v76 offset:30080
	v_add_f32_dpp v49, v49, v49 row_half_mirror row_mask:0xf bank_mask:0xf bound_ctrl:1
	v_pk_fma_f32 v[52:53], v[52:53], v[118:119], v[138:139]
	ds_read_b128 v[36:39], v76 offset:29824
	ds_read_b128 v[40:43], v76 offset:29568
	ds_read_b32 v44, v97 offset:30848
	v_add_f32_dpp v48, v49, v49 row_ror:8 row_mask:0xf bank_mask:0xf bound_ctrl:1
	s_waitcnt lgkmcnt(6)
	v_pk_fma_f32 v[60:61], v[140:141], v[48:49], v[60:61] op_sel_hi:[1,0,1] neg_lo:[0,1,0] neg_hi:[0,1,0]
	v_pk_fma_f32 v[52:53], v[142:143], v[48:49], v[52:53] op_sel_hi:[1,0,1] neg_lo:[0,1,0] neg_hi:[0,1,0]
	v_pk_mul_f32 v[122:123], v[60:61], v[124:125]
	v_pk_fma_f32 v[122:123], v[52:53], v[126:127], v[122:123]
	v_add_f32_e32 v49, v122, v123
	v_pk_mul_f32 v[122:123], v[60:61], v[144:145]
	v_pk_fma_f32 v[122:123], v[52:53], v[146:147], v[122:123]
	ds_read_b128 v[140:143], v76 offset:30336
	v_add_f32_dpp v49, v49, v49 quad_perm:[1,0,3,2] row_mask:0xf bank_mask:0xf bound_ctrl:1
	v_add_f32_e32 v45, v122, v123
	v_pk_mul_f32 v[122:123], v[128:129], v[136:137] op_sel_hi:[1,0]
	ds_read_b128 v[144:147], v76 offset:30592
	v_add_f32_dpp v49, v49, v49 quad_perm:[2,3,0,1] row_mask:0xf bank_mask:0xf bound_ctrl:1
	v_pk_mul_f32 v[138:139], v[130:131], v[136:137] op_sel_hi:[1,0]
	v_pk_fma_f32 v[60:61], v[60:61], v[132:133], v[122:123]
	ds_read_b128 v[108:111], v76 offset:31424
	v_add_f32_dpp v49, v49, v49 row_half_mirror row_mask:0xf bank_mask:0xf bound_ctrl:1
	v_pk_fma_f32 v[52:53], v[52:53], v[134:135], v[138:139]
	ds_read_b128 v[112:115], v76 offset:31168
	ds_read_b128 v[116:119], v76 offset:30912
	ds_read_b32 v120, v97 offset:32192
	v_add_f32_dpp v48, v49, v49 row_ror:8 row_mask:0xf bank_mask:0xf bound_ctrl:1
	s_waitcnt lgkmcnt(6)
	v_pk_fma_f32 v[60:61], v[56:57], v[48:49], v[60:61] op_sel_hi:[1,0,1] neg_lo:[0,1,0] neg_hi:[0,1,0]
	v_pk_fma_f32 v[52:53], v[58:59], v[48:49], v[52:53] op_sel_hi:[1,0,1] neg_lo:[0,1,0] neg_hi:[0,1,0]
	v_pk_mul_f32 v[122:123], v[60:61], v[32:33]
	v_pk_fma_f32 v[122:123], v[52:53], v[34:35], v[122:123]
	v_add_f32_e32 v49, v122, v123
	v_pk_mul_f32 v[122:123], v[60:61], v[64:65]
	v_pk_fma_f32 v[122:123], v[52:53], v[66:67], v[122:123]
	ds_read_b128 v[56:59], v76 offset:31680
	v_add_f32_dpp v49, v49, v49 quad_perm:[1,0,3,2] row_mask:0xf bank_mask:0xf bound_ctrl:1
	v_add_f32_e32 v46, v122, v123
	v_pk_mul_f32 v[122:123], v[36:37], v[44:45] op_sel_hi:[1,0]
	ds_read_b128 v[64:67], v76 offset:31936
	v_add_f32_dpp v49, v49, v49 quad_perm:[2,3,0,1] row_mask:0xf bank_mask:0xf bound_ctrl:1
	v_pk_mul_f32 v[138:139], v[38:39], v[44:45] op_sel_hi:[1,0]
	v_pk_fma_f32 v[60:61], v[60:61], v[40:41], v[122:123]
	ds_read_b128 v[124:127], v76 offset:32768
	v_add_f32_dpp v49, v49, v49 row_half_mirror row_mask:0xf bank_mask:0xf bound_ctrl:1
	v_pk_fma_f32 v[52:53], v[52:53], v[42:43], v[138:139]
	ds_read_b128 v[128:131], v76 offset:32512
	ds_read_b128 v[132:135], v76 offset:32256
	ds_read_b32 v136, v97 offset:33536
	v_add_f32_dpp v48, v49, v49 row_ror:8 row_mask:0xf bank_mask:0xf bound_ctrl:1
	s_waitcnt lgkmcnt(6)
	v_pk_fma_f32 v[60:61], v[140:141], v[48:49], v[60:61] op_sel_hi:[1,0,1] neg_lo:[0,1,0] neg_hi:[0,1,0]
	v_pk_fma_f32 v[52:53], v[142:143], v[48:49], v[52:53] op_sel_hi:[1,0,1] neg_lo:[0,1,0] neg_hi:[0,1,0]
	v_pk_mul_f32 v[122:123], v[60:61], v[108:109]
	v_pk_fma_f32 v[122:123], v[52:53], v[110:111], v[122:123]
	v_add_f32_e32 v49, v122, v123
	v_pk_mul_f32 v[122:123], v[60:61], v[144:145]
	v_pk_fma_f32 v[122:123], v[52:53], v[146:147], v[122:123]
	ds_read_b128 v[140:143], v76 offset:33024
	v_add_f32_dpp v49, v49, v49 quad_perm:[1,0,3,2] row_mask:0xf bank_mask:0xf bound_ctrl:1
	v_add_f32_e32 v47, v122, v123
	v_pk_mul_f32 v[122:123], v[112:113], v[120:121] op_sel_hi:[1,0]
	ds_read_b128 v[144:147], v76 offset:33280
	v_add_f32_dpp v49, v49, v49 quad_perm:[2,3,0,1] row_mask:0xf bank_mask:0xf bound_ctrl:1
	v_pk_mul_f32 v[138:139], v[114:115], v[120:121] op_sel_hi:[1,0]
	v_pk_fma_f32 v[60:61], v[60:61], v[116:117], v[122:123]
	ds_read_b128 v[32:35], v76 offset:34112
	v_add_f32_dpp v49, v49, v49 row_half_mirror row_mask:0xf bank_mask:0xf bound_ctrl:1
	v_pk_fma_f32 v[52:53], v[52:53], v[118:119], v[138:139]
	ds_read_b128 v[36:39], v76 offset:33856
	ds_read_b128 v[40:43], v76 offset:33600
	ds_read_b32 v44, v97 offset:34880
	v_add_f32_dpp v48, v49, v49 row_ror:8 row_mask:0xf bank_mask:0xf bound_ctrl:1
	s_waitcnt lgkmcnt(6)
	v_pk_fma_f32 v[60:61], v[56:57], v[48:49], v[60:61] op_sel_hi:[1,0,1] neg_lo:[0,1,0] neg_hi:[0,1,0]
	v_pk_fma_f32 v[52:53], v[58:59], v[48:49], v[52:53] op_sel_hi:[1,0,1] neg_lo:[0,1,0] neg_hi:[0,1,0]
	v_pk_mul_f32 v[122:123], v[60:61], v[124:125]
	v_pk_fma_f32 v[122:123], v[52:53], v[126:127], v[122:123]
	v_add_f32_e32 v49, v122, v123
	v_pk_mul_f32 v[122:123], v[60:61], v[64:65]
	v_pk_fma_f32 v[122:123], v[52:53], v[66:67], v[122:123]
	ds_read_b128 v[56:59], v76 offset:34368
	v_add_f32_dpp v49, v49, v49 quad_perm:[1,0,3,2] row_mask:0xf bank_mask:0xf bound_ctrl:1
	v_add_f32_e32 v50, v122, v123
	v_pk_mul_f32 v[122:123], v[128:129], v[136:137] op_sel_hi:[1,0]
	ds_read_b128 v[64:67], v76 offset:34624
	v_add_f32_dpp v49, v49, v49 quad_perm:[2,3,0,1] row_mask:0xf bank_mask:0xf bound_ctrl:1
	v_pk_mul_f32 v[138:139], v[130:131], v[136:137] op_sel_hi:[1,0]
	v_pk_fma_f32 v[60:61], v[60:61], v[132:133], v[122:123]
	ds_read_b128 v[108:111], v76 offset:35456
	v_add_f32_dpp v49, v49, v49 row_half_mirror row_mask:0xf bank_mask:0xf bound_ctrl:1
	v_pk_fma_f32 v[52:53], v[52:53], v[134:135], v[138:139]
	ds_read_b128 v[112:115], v76 offset:35200
	ds_read_b128 v[116:119], v76 offset:34944
	ds_read_b32 v120, v97 offset:36224
	v_add_f32_dpp v48, v49, v49 row_ror:8 row_mask:0xf bank_mask:0xf bound_ctrl:1
	s_waitcnt lgkmcnt(6)
	v_pk_fma_f32 v[60:61], v[140:141], v[48:49], v[60:61] op_sel_hi:[1,0,1] neg_lo:[0,1,0] neg_hi:[0,1,0]
	v_pk_fma_f32 v[52:53], v[142:143], v[48:49], v[52:53] op_sel_hi:[1,0,1] neg_lo:[0,1,0] neg_hi:[0,1,0]
	v_pk_mul_f32 v[122:123], v[60:61], v[32:33]
	v_pk_fma_f32 v[122:123], v[52:53], v[34:35], v[122:123]
	v_add_f32_e32 v49, v122, v123
	v_pk_mul_f32 v[122:123], v[60:61], v[144:145]
	v_pk_fma_f32 v[122:123], v[52:53], v[146:147], v[122:123]
	ds_read_b128 v[140:143], v76 offset:35712
	v_add_f32_dpp v49, v49, v49 quad_perm:[1,0,3,2] row_mask:0xf bank_mask:0xf bound_ctrl:1
	v_add_f32_e32 v51, v122, v123
	v_pk_mul_f32 v[122:123], v[36:37], v[44:45] op_sel_hi:[1,0]
	ds_read_b128 v[144:147], v76 offset:35968
	v_add_f32_dpp v49, v49, v49 quad_perm:[2,3,0,1] row_mask:0xf bank_mask:0xf bound_ctrl:1
	v_pk_mul_f32 v[138:139], v[38:39], v[44:45] op_sel_hi:[1,0]
	v_pk_fma_f32 v[60:61], v[60:61], v[40:41], v[122:123]
	ds_read_b128 v[124:127], v76 offset:36800
	v_add_f32_dpp v49, v49, v49 row_half_mirror row_mask:0xf bank_mask:0xf bound_ctrl:1
	v_pk_fma_f32 v[52:53], v[52:53], v[42:43], v[138:139]
	ds_read_b128 v[128:131], v76 offset:36544
	ds_read_b128 v[132:135], v76 offset:36288
	ds_read_b32 v136, v97 offset:37568
	v_add_f32_dpp v48, v49, v49 row_ror:8 row_mask:0xf bank_mask:0xf bound_ctrl:1
	s_waitcnt lgkmcnt(6)
	v_pk_fma_f32 v[60:61], v[56:57], v[48:49], v[60:61] op_sel_hi:[1,0,1] neg_lo:[0,1,0] neg_hi:[0,1,0]
	v_pk_fma_f32 v[52:53], v[58:59], v[48:49], v[52:53] op_sel_hi:[1,0,1] neg_lo:[0,1,0] neg_hi:[0,1,0]
	v_pk_mul_f32 v[122:123], v[60:61], v[108:109]
	v_pk_fma_f32 v[122:123], v[52:53], v[110:111], v[122:123]
	v_add_f32_e32 v49, v122, v123
	v_pk_mul_f32 v[122:123], v[60:61], v[64:65]
	v_pk_fma_f32 v[122:123], v[52:53], v[66:67], v[122:123]
	ds_read_b128 v[56:59], v76 offset:37056
	v_add_f32_dpp v49, v49, v49 quad_perm:[1,0,3,2] row_mask:0xf bank_mask:0xf bound_ctrl:1
	v_add_f32_e32 v54, v122, v123
	v_pk_mul_f32 v[122:123], v[112:113], v[120:121] op_sel_hi:[1,0]
	ds_read_b128 v[64:67], v76 offset:37312
	v_add_f32_dpp v49, v49, v49 quad_perm:[2,3,0,1] row_mask:0xf bank_mask:0xf bound_ctrl:1
	v_pk_mul_f32 v[138:139], v[114:115], v[120:121] op_sel_hi:[1,0]
	v_pk_fma_f32 v[60:61], v[60:61], v[116:117], v[122:123]
	ds_read_b128 v[32:35], v76 offset:38144
	v_add_f32_dpp v49, v49, v49 row_half_mirror row_mask:0xf bank_mask:0xf bound_ctrl:1
	v_pk_fma_f32 v[52:53], v[52:53], v[118:119], v[138:139]
	ds_read_b128 v[36:39], v76 offset:37888
	ds_read_b128 v[40:43], v76 offset:37632
	ds_read_b32 v44, v97 offset:38912
	v_add_f32_dpp v48, v49, v49 row_ror:8 row_mask:0xf bank_mask:0xf bound_ctrl:1
	s_waitcnt lgkmcnt(6)
	v_pk_fma_f32 v[60:61], v[140:141], v[48:49], v[60:61] op_sel_hi:[1,0,1] neg_lo:[0,1,0] neg_hi:[0,1,0]
	v_pk_fma_f32 v[52:53], v[142:143], v[48:49], v[52:53] op_sel_hi:[1,0,1] neg_lo:[0,1,0] neg_hi:[0,1,0]
	v_pk_mul_f32 v[122:123], v[60:61], v[124:125]
	v_pk_fma_f32 v[122:123], v[52:53], v[126:127], v[122:123]
	v_add_f32_e32 v49, v122, v123
	v_pk_mul_f32 v[122:123], v[60:61], v[144:145]
	v_pk_fma_f32 v[122:123], v[52:53], v[146:147], v[122:123]
	ds_read_b128 v[140:143], v76 offset:38400
	v_add_f32_dpp v49, v49, v49 quad_perm:[1,0,3,2] row_mask:0xf bank_mask:0xf bound_ctrl:1
	v_add_f32_e32 v55, v122, v123
	v_pk_mul_f32 v[122:123], v[128:129], v[136:137] op_sel_hi:[1,0]
	ds_read_b128 v[144:147], v76 offset:38656
	v_add_f32_dpp v49, v49, v49 quad_perm:[2,3,0,1] row_mask:0xf bank_mask:0xf bound_ctrl:1
	v_pk_mul_f32 v[138:139], v[130:131], v[136:137] op_sel_hi:[1,0]
	v_pk_fma_f32 v[60:61], v[60:61], v[132:133], v[122:123]
	ds_read_b128 v[108:111], v76 offset:39488
	v_add_f32_dpp v49, v49, v49 row_half_mirror row_mask:0xf bank_mask:0xf bound_ctrl:1
	v_pk_fma_f32 v[52:53], v[52:53], v[134:135], v[138:139]
	ds_read_b128 v[112:115], v76 offset:39232
	ds_read_b128 v[116:119], v76 offset:38976
	ds_read_b32 v120, v97 offset:40256
	v_add_f32_dpp v48, v49, v49 row_ror:8 row_mask:0xf bank_mask:0xf bound_ctrl:1
	s_waitcnt lgkmcnt(6)
	v_pk_fma_f32 v[60:61], v[56:57], v[48:49], v[60:61] op_sel_hi:[1,0,1] neg_lo:[0,1,0] neg_hi:[0,1,0]
	v_pk_fma_f32 v[52:53], v[58:59], v[48:49], v[52:53] op_sel_hi:[1,0,1] neg_lo:[0,1,0] neg_hi:[0,1,0]
	v_pk_mul_f32 v[122:123], v[60:61], v[32:33]
	v_pk_fma_f32 v[122:123], v[52:53], v[34:35], v[122:123]
	v_add_f32_e32 v49, v122, v123
	v_pk_mul_f32 v[122:123], v[60:61], v[64:65]
	v_pk_fma_f32 v[122:123], v[52:53], v[66:67], v[122:123]
	ds_read_b128 v[56:59], v76 offset:39744
	v_add_f32_dpp v49, v49, v49 quad_perm:[1,0,3,2] row_mask:0xf bank_mask:0xf bound_ctrl:1
	v_add_f32_e32 v62, v122, v123
	v_pk_mul_f32 v[122:123], v[36:37], v[44:45] op_sel_hi:[1,0]
	ds_read_b128 v[64:67], v76 offset:40000
	v_add_f32_dpp v49, v49, v49 quad_perm:[2,3,0,1] row_mask:0xf bank_mask:0xf bound_ctrl:1
	v_pk_mul_f32 v[138:139], v[38:39], v[44:45] op_sel_hi:[1,0]
	v_pk_fma_f32 v[60:61], v[60:61], v[40:41], v[122:123]
	ds_read_b128 v[124:127], v76 offset:40832
	v_add_f32_dpp v49, v49, v49 row_half_mirror row_mask:0xf bank_mask:0xf bound_ctrl:1
	v_pk_fma_f32 v[52:53], v[52:53], v[42:43], v[138:139]
	ds_read_b128 v[128:131], v76 offset:40576
	ds_read_b128 v[132:135], v76 offset:40320
	ds_read_b32 v136, v97 offset:41600
	v_add_f32_dpp v48, v49, v49 row_ror:8 row_mask:0xf bank_mask:0xf bound_ctrl:1
	s_waitcnt lgkmcnt(6)
	v_pk_fma_f32 v[60:61], v[140:141], v[48:49], v[60:61] op_sel_hi:[1,0,1] neg_lo:[0,1,0] neg_hi:[0,1,0]
	v_pk_fma_f32 v[52:53], v[142:143], v[48:49], v[52:53] op_sel_hi:[1,0,1] neg_lo:[0,1,0] neg_hi:[0,1,0]
	v_pk_mul_f32 v[122:123], v[60:61], v[108:109]
	v_pk_fma_f32 v[122:123], v[52:53], v[110:111], v[122:123]
	v_add_f32_e32 v49, v122, v123
	v_pk_mul_f32 v[122:123], v[60:61], v[144:145]
	v_pk_fma_f32 v[122:123], v[52:53], v[146:147], v[122:123]
	ds_read_b128 v[140:143], v76 offset:41088
	v_add_f32_dpp v49, v49, v49 quad_perm:[1,0,3,2] row_mask:0xf bank_mask:0xf bound_ctrl:1
	v_add_f32_e32 v63, v122, v123
	v_pk_mul_f32 v[122:123], v[112:113], v[120:121] op_sel_hi:[1,0]
	ds_read_b128 v[144:147], v76 offset:41344
	v_add_f32_dpp v49, v49, v49 quad_perm:[2,3,0,1] row_mask:0xf bank_mask:0xf bound_ctrl:1
	v_pk_mul_f32 v[138:139], v[114:115], v[120:121] op_sel_hi:[1,0]
	v_pk_fma_f32 v[60:61], v[60:61], v[116:117], v[122:123]
	ds_read_b128 v[32:35], v76 offset:42176
	v_add_f32_dpp v49, v49, v49 row_half_mirror row_mask:0xf bank_mask:0xf bound_ctrl:1
	v_pk_fma_f32 v[52:53], v[52:53], v[118:119], v[138:139]
	ds_read_b128 v[36:39], v76 offset:41920
	ds_read_b128 v[40:43], v76 offset:41664
	ds_read_b32 v44, v97 offset:42944
	v_add_f32_dpp v48, v49, v49 row_ror:8 row_mask:0xf bank_mask:0xf bound_ctrl:1
	s_waitcnt lgkmcnt(6)
	v_pk_fma_f32 v[60:61], v[56:57], v[48:49], v[60:61] op_sel_hi:[1,0,1] neg_lo:[0,1,0] neg_hi:[0,1,0]
	v_pk_fma_f32 v[52:53], v[58:59], v[48:49], v[52:53] op_sel_hi:[1,0,1] neg_lo:[0,1,0] neg_hi:[0,1,0]
	v_pk_mul_f32 v[122:123], v[60:61], v[124:125]
	v_pk_fma_f32 v[122:123], v[52:53], v[126:127], v[122:123]
	v_add_f32_e32 v49, v122, v123
	v_pk_mul_f32 v[122:123], v[60:61], v[64:65]
	v_pk_fma_f32 v[122:123], v[52:53], v[66:67], v[122:123]
	ds_read_b128 v[56:59], v76 offset:42432
	v_add_f32_dpp v49, v49, v49 quad_perm:[1,0,3,2] row_mask:0xf bank_mask:0xf bound_ctrl:1
	v_add_f32_e32 v68, v122, v123
	v_pk_mul_f32 v[122:123], v[128:129], v[136:137] op_sel_hi:[1,0]
	ds_read_b128 v[64:67], v76 offset:42688
	v_add_f32_dpp v49, v49, v49 quad_perm:[2,3,0,1] row_mask:0xf bank_mask:0xf bound_ctrl:1
	v_pk_mul_f32 v[138:139], v[130:131], v[136:137] op_sel_hi:[1,0]
	v_pk_fma_f32 v[60:61], v[60:61], v[132:133], v[122:123]
	v_add_f32_dpp v49, v49, v49 row_half_mirror row_mask:0xf bank_mask:0xf bound_ctrl:1
	v_pk_fma_f32 v[52:53], v[52:53], v[134:135], v[138:139]
	s_nop 0
	v_add_f32_dpp v48, v49, v49 row_ror:8 row_mask:0xf bank_mask:0xf bound_ctrl:1
	s_waitcnt lgkmcnt(2)
	v_pk_fma_f32 v[60:61], v[140:141], v[48:49], v[60:61] op_sel_hi:[1,0,1] neg_lo:[0,1,0] neg_hi:[0,1,0]
	v_pk_fma_f32 v[52:53], v[142:143], v[48:49], v[52:53] op_sel_hi:[1,0,1] neg_lo:[0,1,0] neg_hi:[0,1,0]
	v_pk_mul_f32 v[122:123], v[60:61], v[32:33]
	v_pk_fma_f32 v[122:123], v[52:53], v[34:35], v[122:123]
	v_add_f32_e32 v49, v122, v123
	v_pk_mul_f32 v[122:123], v[60:61], v[144:145]
	v_pk_fma_f32 v[122:123], v[52:53], v[146:147], v[122:123]
	v_add_f32_dpp v49, v49, v49 quad_perm:[1,0,3,2] row_mask:0xf bank_mask:0xf bound_ctrl:1
	v_add_f32_e32 v88, v122, v123
	v_pk_mul_f32 v[122:123], v[36:37], v[44:45] op_sel_hi:[1,0]
	v_add_f32_dpp v49, v49, v49 quad_perm:[2,3,0,1] row_mask:0xf bank_mask:0xf bound_ctrl:1
	v_pk_mul_f32 v[138:139], v[38:39], v[44:45] op_sel_hi:[1,0]
	v_pk_fma_f32 v[60:61], v[60:61], v[40:41], v[122:123]
	v_add_f32_dpp v49, v49, v49 row_half_mirror row_mask:0xf bank_mask:0xf bound_ctrl:1
	v_pk_fma_f32 v[52:53], v[52:53], v[42:43], v[138:139]
	s_nop 0
	v_add_f32_dpp v48, v49, v49 row_ror:8 row_mask:0xf bank_mask:0xf bound_ctrl:1
	s_waitcnt lgkmcnt(0)
	v_pk_fma_f32 v[60:61], v[56:57], v[48:49], v[60:61] op_sel_hi:[1,0,1] neg_lo:[0,1,0] neg_hi:[0,1,0]
	v_pk_fma_f32 v[52:53], v[58:59], v[48:49], v[52:53] op_sel_hi:[1,0,1] neg_lo:[0,1,0] neg_hi:[0,1,0]
	v_pk_mul_f32 v[122:123], v[60:61], v[64:65]
	v_pk_fma_f32 v[122:123], v[52:53], v[66:67], v[122:123]
	v_add_f32_e32 v107, v122, v123
	v_add_f32_dpp v90, v90, v90 row_ror:8 row_mask:0xf bank_mask:0x3
	v_add_f32_dpp v91, v91, v91 row_ror:8 row_mask:0xf bank_mask:0x3
	v_add_f32_dpp v92, v92, v92 row_ror:8 row_mask:0xf bank_mask:0x3
	v_add_f32_dpp v93, v93, v93 row_ror:8 row_mask:0xf bank_mask:0x3
	v_add_f32_dpp v45, v45, v45 row_ror:8 row_mask:0xf bank_mask:0x3
	v_add_f32_dpp v46, v46, v46 row_ror:8 row_mask:0xf bank_mask:0x3
	v_add_f32_dpp v47, v47, v47 row_ror:8 row_mask:0xf bank_mask:0x3
	v_add_f32_dpp v50, v50, v50 row_ror:8 row_mask:0xf bank_mask:0x3
	v_add_f32_dpp v90, v51, v51 row_ror:8 row_mask:0xf bank_mask:0xc
	v_add_f32_dpp v91, v54, v54 row_ror:8 row_mask:0xf bank_mask:0xc
	v_add_f32_dpp v92, v55, v55 row_ror:8 row_mask:0xf bank_mask:0xc
	v_add_f32_dpp v93, v62, v62 row_ror:8 row_mask:0xf bank_mask:0xc
	v_add_f32_dpp v45, v63, v63 row_ror:8 row_mask:0xf bank_mask:0xc
	v_add_f32_dpp v46, v68, v68 row_ror:8 row_mask:0xf bank_mask:0xc
	v_add_f32_dpp v47, v88, v88 row_ror:8 row_mask:0xf bank_mask:0xc
	v_add_f32_dpp v50, v107, v107 row_ror:8 row_mask:0xf bank_mask:0xc
	v_add_f32_dpp v90, v90, v90 row_ror:12 row_mask:0xf bank_mask:0x5
	v_add_f32_dpp v91, v91, v91 row_ror:12 row_mask:0xf bank_mask:0x5
	v_add_f32_dpp v92, v92, v92 row_ror:12 row_mask:0xf bank_mask:0x5
	v_add_f32_dpp v93, v93, v93 row_ror:12 row_mask:0xf bank_mask:0x5
	v_add_f32_dpp v90, v45, v45 row_ror:4 row_mask:0xf bank_mask:0xa
	v_add_f32_dpp v91, v46, v46 row_ror:4 row_mask:0xf bank_mask:0xa
	v_add_f32_dpp v92, v47, v47 row_ror:4 row_mask:0xf bank_mask:0xa
	v_add_f32_dpp v93, v50, v50 row_ror:4 row_mask:0xf bank_mask:0xa
	s_mov_b32 vcc_lo, 0xcccccccc
	s_mov_b32 vcc_hi, 0xcccccccc
	v_cndmask_b32_e32 v51, v92, v90, vcc
	v_cndmask_b32_e32 v54, v93, v91, vcc
	v_cndmask_b32_e32 v55, v90, v92, vcc
	v_cndmask_b32_e32 v62, v91, v93, vcc
	v_add_f32_dpp v90, v51, v55 quad_perm:[2,3,0,1] row_mask:0xf bank_mask:0xf
	v_add_f32_dpp v91, v54, v62 quad_perm:[2,3,0,1] row_mask:0xf bank_mask:0xf
	s_mov_b32 vcc_lo, 0xaaaaaaaa
	s_mov_b32 vcc_hi, 0xaaaaaaaa
	v_cndmask_b32_e32 v51, v91, v90, vcc
	v_cndmask_b32_e32 v55, v90, v91, vcc
	s_nop 1
	v_add_f32_dpp v109, v51, v55 quad_perm:[1,0,3,2] row_mask:0xf bank_mask:0xf
